# layer-1 weight conversion loops: all 32 loads of an item issued before the LDS writes (was 2 loads + vmcnt(0))
# speedup vs baseline: 1.0229x; 1.0025x over previous
.LBB0_454:
	v_lshl_add_u64 v[60:61], v[44:45], 0, s[6:7]
	global_load_dword v72, v[60:61], off nt
	v_lshl_add_u64 v[60:61], v[42:43], 0, s[6:7]
	global_load_dword v73, v[60:61], off nt
	v_lshl_add_u64 v[60:61], v[40:41], 0, s[6:7]
	global_load_dword v74, v[60:61], off nt
	v_lshl_add_u64 v[60:61], v[38:39], 0, s[6:7]
	global_load_dword v75, v[60:61], off nt
	v_lshl_add_u64 v[60:61], v[36:37], 0, s[6:7]
	global_load_dword v76, v[60:61], off nt
	v_lshl_add_u64 v[60:61], v[34:35], 0, s[6:7]
	global_load_dword v77, v[60:61], off nt
	v_lshl_add_u64 v[60:61], v[32:33], 0, s[6:7]
	global_load_dword v78, v[60:61], off nt
	v_lshl_add_u64 v[60:61], v[30:31], 0, s[6:7]
	global_load_dword v79, v[60:61], off nt
	s_add_u32 s6, s6, 0x10000
	s_addc_u32 s7, s7, 0
	v_lshl_add_u64 v[60:61], v[44:45], 0, s[6:7]
	global_load_dword v80, v[60:61], off nt
	v_lshl_add_u64 v[60:61], v[42:43], 0, s[6:7]
	global_load_dword v81, v[60:61], off nt
	v_lshl_add_u64 v[60:61], v[40:41], 0, s[6:7]
	global_load_dword v82, v[60:61], off nt
	v_lshl_add_u64 v[60:61], v[38:39], 0, s[6:7]
	global_load_dword v83, v[60:61], off nt
	v_lshl_add_u64 v[60:61], v[36:37], 0, s[6:7]
	global_load_dword v84, v[60:61], off nt
	v_lshl_add_u64 v[60:61], v[34:35], 0, s[6:7]
	global_load_dword v85, v[60:61], off nt
	v_lshl_add_u64 v[60:61], v[32:33], 0, s[6:7]
	global_load_dword v86, v[60:61], off nt
	v_lshl_add_u64 v[60:61], v[30:31], 0, s[6:7]
	global_load_dword v87, v[60:61], off nt
	s_add_u32 s6, s6, 0x10000
	s_addc_u32 s7, s7, 0
	v_lshl_add_u64 v[60:61], v[44:45], 0, s[6:7]
	global_load_dword v88, v[60:61], off nt
	v_lshl_add_u64 v[60:61], v[42:43], 0, s[6:7]
	global_load_dword v89, v[60:61], off nt
	v_lshl_add_u64 v[60:61], v[40:41], 0, s[6:7]
	global_load_dword v90, v[60:61], off nt
	v_lshl_add_u64 v[60:61], v[38:39], 0, s[6:7]
	global_load_dword v91, v[60:61], off nt
	v_lshl_add_u64 v[60:61], v[36:37], 0, s[6:7]
	global_load_dword v92, v[60:61], off nt
	v_lshl_add_u64 v[60:61], v[34:35], 0, s[6:7]
	global_load_dword v93, v[60:61], off nt
	v_lshl_add_u64 v[60:61], v[32:33], 0, s[6:7]
	global_load_dword v94, v[60:61], off nt
	v_lshl_add_u64 v[60:61], v[30:31], 0, s[6:7]
	global_load_dword v95, v[60:61], off nt
	s_add_u32 s6, s6, 0x10000
	s_addc_u32 s7, s7, 0
	v_lshl_add_u64 v[60:61], v[44:45], 0, s[6:7]
	global_load_dword v96, v[60:61], off nt
	v_lshl_add_u64 v[60:61], v[42:43], 0, s[6:7]
	global_load_dword v97, v[60:61], off nt
	v_lshl_add_u64 v[60:61], v[40:41], 0, s[6:7]
	global_load_dword v98, v[60:61], off nt
	v_lshl_add_u64 v[60:61], v[38:39], 0, s[6:7]
	global_load_dword v99, v[60:61], off nt
	v_lshl_add_u64 v[60:61], v[36:37], 0, s[6:7]
	global_load_dword v100, v[60:61], off nt
	v_lshl_add_u64 v[60:61], v[34:35], 0, s[6:7]
	global_load_dword v101, v[60:61], off nt
	v_lshl_add_u64 v[60:61], v[32:33], 0, s[6:7]
	global_load_dword v102, v[60:61], off nt
	v_lshl_add_u64 v[60:61], v[30:31], 0, s[6:7]
	global_load_dword v103, v[60:61], off nt
	s_add_u32 s6, s6, 0x10000
	s_addc_u32 s7, s7, 0
	v_add_u32_e32 v63, 0x400, v0
	s_waitcnt vmcnt(30)
	ds_write2_b32 v0, v72, v73 offset1:66
	s_waitcnt vmcnt(28)
	ds_write2_b32 v0, v74, v75 offset0:132 offset1:198
	s_waitcnt vmcnt(26)
	ds_write2_b32 v63, v76, v77 offset0:8 offset1:74
	s_waitcnt vmcnt(24)
	ds_write2_b32 v63, v78, v79 offset0:140 offset1:206
	v_add_u32_e32 v0, 0x840, v0
	v_add_u32_e32 v63, 0x400, v0
	s_waitcnt vmcnt(22)
	ds_write2_b32 v0, v80, v81 offset1:66
	s_waitcnt vmcnt(20)
	ds_write2_b32 v0, v82, v83 offset0:132 offset1:198
	s_waitcnt vmcnt(18)
	ds_write2_b32 v63, v84, v85 offset0:8 offset1:74
	s_waitcnt vmcnt(16)
	ds_write2_b32 v63, v86, v87 offset0:140 offset1:206
	v_add_u32_e32 v0, 0x840, v0
	v_add_u32_e32 v63, 0x400, v0
	s_waitcnt vmcnt(14)
	ds_write2_b32 v0, v88, v89 offset1:66
	s_waitcnt vmcnt(12)
	ds_write2_b32 v0, v90, v91 offset0:132 offset1:198
	s_waitcnt vmcnt(10)
	ds_write2_b32 v63, v92, v93 offset0:8 offset1:74
	s_waitcnt vmcnt(8)
	ds_write2_b32 v63, v94, v95 offset0:140 offset1:206
	v_add_u32_e32 v0, 0x840, v0
	v_add_u32_e32 v63, 0x400, v0
	s_waitcnt vmcnt(6)
	ds_write2_b32 v0, v96, v97 offset1:66
	s_waitcnt vmcnt(4)
	ds_write2_b32 v0, v98, v99 offset0:132 offset1:198
	s_waitcnt vmcnt(2)
	ds_write2_b32 v63, v100, v101 offset0:8 offset1:74
	s_waitcnt vmcnt(0)
	ds_write2_b32 v63, v102, v103 offset0:140 offset1:206
	v_add_u32_e32 v0, 0x840, v0
	s_lshl_b32 s0, s16, 1
	s_waitcnt lgkmcnt(0)
	s_add_i32 s0, s0, 0x19a00
	s_lshl_b32 s6, s16, 5
	ds_read2_b32 v[36:37], v48 offset0:33 offset1:41
	ds_read2_b32 v[38:39], v48 offset1:8
	ds_read2_b32 v[40:41], v48 offset0:66 offset1:74
	ds_read2_b32 v[42:43], v48 offset0:99 offset1:107
	ds_read2_b32 v[44:45], v48 offset0:132 offset1:140
	ds_read2_b32 v[60:61], v48 offset0:165 offset1:173
	ds_read2_b32 v[62:63], v48 offset0:198 offset1:206
	ds_read2_b32 v[64:65], v48 offset0:231 offset1:239
	s_and_b32 s0, s0, 0x1ffc0
	s_and_b32 s6, s6, 0x3e0
	s_lshl_b32 s0, s0, 1
	v_or_b32_e32 v0, s6, v47
	v_lshl_add_u64 v[34:35], v[2:3], 0, s[0:1]
	v_lshlrev_b32_e32 v0, 11, v0
	v_lshl_add_u64 v[66:67], v[34:35], 0, v[0:1]
	v_or_b32_e32 v0, s6, v49
	s_waitcnt lgkmcnt(6)
	v_cvt_pk_bf16_f32 v30, v38, v36
	s_waitcnt lgkmcnt(4)
	v_cvt_pk_bf16_f32 v31, v40, v42
	s_waitcnt lgkmcnt(2)
	v_cvt_pk_bf16_f32 v32, v44, v60
	s_waitcnt lgkmcnt(0)
	v_cvt_pk_bf16_f32 v33, v62, v64
	v_lshlrev_b32_e32 v0, 11, v0
	global_store_dwordx4 v[66:67], v[30:33], off
	s_nop 1
	v_cvt_pk_bf16_f32 v30, v39, v37
	v_cvt_pk_bf16_f32 v31, v41, v43
	v_cvt_pk_bf16_f32 v32, v45, v61
	v_cvt_pk_bf16_f32 v33, v63, v65
	v_lshl_add_u64 v[36:37], v[34:35], 0, v[0:1]
	global_store_dwordx4 v[36:37], v[30:33], off
	ds_read2_b32 v[36:37], v48 offset0:49 offset1:57
	ds_read2_b32 v[38:39], v48 offset0:16 offset1:24
	ds_read2_b32 v[40:41], v48 offset0:82 offset1:90
	ds_read2_b32 v[42:43], v48 offset0:115 offset1:123
	ds_read2_b32 v[44:45], v48 offset0:148 offset1:156
	ds_read2_b32 v[60:61], v48 offset0:181 offset1:189
	ds_read2_b32 v[62:63], v48 offset0:214 offset1:222
	ds_read2_b32 v[64:65], v48 offset0:247 offset1:255
	v_or_b32_e32 v0, s6, v50
	v_lshlrev_b32_e32 v0, 11, v0
	v_lshl_add_u64 v[66:67], v[34:35], 0, v[0:1]
	v_or_b32_e32 v0, s6, v51
	s_waitcnt lgkmcnt(6)
	v_cvt_pk_bf16_f32 v30, v38, v36
	s_waitcnt lgkmcnt(4)
	v_cvt_pk_bf16_f32 v31, v40, v42
	s_waitcnt lgkmcnt(2)
	v_cvt_pk_bf16_f32 v32, v44, v60
	s_waitcnt lgkmcnt(0)
	v_cvt_pk_bf16_f32 v33, v62, v64
	v_lshlrev_b32_e32 v0, 11, v0
	global_store_dwordx4 v[66:67], v[30:33], off
	v_lshl_add_u64 v[34:35], v[34:35], 0, v[0:1]
	s_mov_b64 s[6:7], 0
	v_cvt_pk_bf16_f32 v30, v39, v37
	v_cvt_pk_bf16_f32 v31, v41, v43
	v_cvt_pk_bf16_f32 v32, v45, v61
	v_cvt_pk_bf16_f32 v33, v63, v65
	global_store_dwordx4 v[34:35], v[30:33], off
	s_waitcnt lgkmcnt(0)

.LBB0_458:
	v_lshl_add_u64 v[60:61], v[44:45], 0, s[6:7]
	global_load_dword v72, v[60:61], off nt
	v_lshl_add_u64 v[60:61], v[42:43], 0, s[6:7]
	global_load_dword v73, v[60:61], off nt
	v_lshl_add_u64 v[60:61], v[40:41], 0, s[6:7]
	global_load_dword v74, v[60:61], off nt
	v_lshl_add_u64 v[60:61], v[38:39], 0, s[6:7]
	global_load_dword v75, v[60:61], off nt
	v_lshl_add_u64 v[60:61], v[36:37], 0, s[6:7]
	global_load_dword v76, v[60:61], off nt
	v_lshl_add_u64 v[60:61], v[34:35], 0, s[6:7]
	global_load_dword v77, v[60:61], off nt
	v_lshl_add_u64 v[60:61], v[32:33], 0, s[6:7]
	global_load_dword v78, v[60:61], off nt
	v_lshl_add_u64 v[60:61], v[30:31], 0, s[6:7]
	global_load_dword v79, v[60:61], off nt
	s_add_u32 s6, s6, 0x30000
	s_addc_u32 s7, s7, 0
	v_lshl_add_u64 v[60:61], v[44:45], 0, s[6:7]
	global_load_dword v80, v[60:61], off nt
	v_lshl_add_u64 v[60:61], v[42:43], 0, s[6:7]
	global_load_dword v81, v[60:61], off nt
	v_lshl_add_u64 v[60:61], v[40:41], 0, s[6:7]
	global_load_dword v82, v[60:61], off nt
	v_lshl_add_u64 v[60:61], v[38:39], 0, s[6:7]
	global_load_dword v83, v[60:61], off nt
	v_lshl_add_u64 v[60:61], v[36:37], 0, s[6:7]
	global_load_dword v84, v[60:61], off nt
	v_lshl_add_u64 v[60:61], v[34:35], 0, s[6:7]
	global_load_dword v85, v[60:61], off nt
	v_lshl_add_u64 v[60:61], v[32:33], 0, s[6:7]
	global_load_dword v86, v[60:61], off nt
	v_lshl_add_u64 v[60:61], v[30:31], 0, s[6:7]
	global_load_dword v87, v[60:61], off nt
	s_add_u32 s6, s6, 0x30000
	s_addc_u32 s7, s7, 0
	v_lshl_add_u64 v[60:61], v[44:45], 0, s[6:7]
	global_load_dword v88, v[60:61], off nt
	v_lshl_add_u64 v[60:61], v[42:43], 0, s[6:7]
	global_load_dword v89, v[60:61], off nt
	v_lshl_add_u64 v[60:61], v[40:41], 0, s[6:7]
	global_load_dword v90, v[60:61], off nt
	v_lshl_add_u64 v[60:61], v[38:39], 0, s[6:7]
	global_load_dword v91, v[60:61], off nt
	v_lshl_add_u64 v[60:61], v[36:37], 0, s[6:7]
	global_load_dword v92, v[60:61], off nt
	v_lshl_add_u64 v[60:61], v[34:35], 0, s[6:7]
	global_load_dword v93, v[60:61], off nt
	v_lshl_add_u64 v[60:61], v[32:33], 0, s[6:7]
	global_load_dword v94, v[60:61], off nt
	v_lshl_add_u64 v[60:61], v[30:31], 0, s[6:7]
	global_load_dword v95, v[60:61], off nt
	s_add_u32 s6, s6, 0x30000
	s_addc_u32 s7, s7, 0
	v_lshl_add_u64 v[60:61], v[44:45], 0, s[6:7]
	global_load_dword v96, v[60:61], off nt
	v_lshl_add_u64 v[60:61], v[42:43], 0, s[6:7]
	global_load_dword v97, v[60:61], off nt
	v_lshl_add_u64 v[60:61], v[40:41], 0, s[6:7]
	global_load_dword v98, v[60:61], off nt
	v_lshl_add_u64 v[60:61], v[38:39], 0, s[6:7]
	global_load_dword v99, v[60:61], off nt
	v_lshl_add_u64 v[60:61], v[36:37], 0, s[6:7]
	global_load_dword v100, v[60:61], off nt
	v_lshl_add_u64 v[60:61], v[34:35], 0, s[6:7]
	global_load_dword v101, v[60:61], off nt
	v_lshl_add_u64 v[60:61], v[32:33], 0, s[6:7]
	global_load_dword v102, v[60:61], off nt
	v_lshl_add_u64 v[60:61], v[30:31], 0, s[6:7]
	global_load_dword v103, v[60:61], off nt
	s_add_u32 s6, s6, 0x30000
	s_addc_u32 s7, s7, 0
	v_add_u32_e32 v63, 0x400, v0
	s_waitcnt vmcnt(30)
	ds_write2_b32 v0, v72, v73 offset1:66
	s_waitcnt vmcnt(28)
	ds_write2_b32 v0, v74, v75 offset0:132 offset1:198
	s_waitcnt vmcnt(26)
	ds_write2_b32 v63, v76, v77 offset0:8 offset1:74
	s_waitcnt vmcnt(24)
	ds_write2_b32 v63, v78, v79 offset0:140 offset1:206
	v_add_u32_e32 v0, 0x840, v0
	v_add_u32_e32 v63, 0x400, v0
	s_waitcnt vmcnt(22)
	ds_write2_b32 v0, v80, v81 offset1:66
	s_waitcnt vmcnt(20)
	ds_write2_b32 v0, v82, v83 offset0:132 offset1:198
	s_waitcnt vmcnt(18)
	ds_write2_b32 v63, v84, v85 offset0:8 offset1:74
	s_waitcnt vmcnt(16)
	ds_write2_b32 v63, v86, v87 offset0:140 offset1:206
	v_add_u32_e32 v0, 0x840, v0
	v_add_u32_e32 v63, 0x400, v0
	s_waitcnt vmcnt(14)
	ds_write2_b32 v0, v88, v89 offset1:66
	s_waitcnt vmcnt(12)
	ds_write2_b32 v0, v90, v91 offset0:132 offset1:198
	s_waitcnt vmcnt(10)
	ds_write2_b32 v63, v92, v93 offset0:8 offset1:74
	s_waitcnt vmcnt(8)
	ds_write2_b32 v63, v94, v95 offset0:140 offset1:206
	v_add_u32_e32 v0, 0x840, v0
	v_add_u32_e32 v63, 0x400, v0
	s_waitcnt vmcnt(6)
	ds_write2_b32 v0, v96, v97 offset1:66
	s_waitcnt vmcnt(4)
	ds_write2_b32 v0, v98, v99 offset0:132 offset1:198
	s_waitcnt vmcnt(2)
	ds_write2_b32 v63, v100, v101 offset0:8 offset1:74
	s_waitcnt vmcnt(0)
	ds_write2_b32 v63, v102, v103 offset0:140 offset1:206
	v_add_u32_e32 v0, 0x840, v0
	s_waitcnt lgkmcnt(0)
	ds_read2_b32 v[36:37], v48 offset0:33 offset1:41
	ds_read2_b32 v[38:39], v48 offset1:8
	ds_read2_b32 v[40:41], v48 offset0:66 offset1:74
	ds_read2_b32 v[42:43], v48 offset0:99 offset1:107
	ds_read2_b32 v[44:45], v48 offset0:132 offset1:140
	ds_read2_b32 v[60:61], v48 offset0:165 offset1:173
	ds_read2_b32 v[62:63], v48 offset0:198 offset1:206
	ds_read2_b32 v[64:65], v48 offset0:231 offset1:239
	s_and_b32 s6, 0xffff, s10
	s_and_b32 s0, 0xffff, s9
	s_lshl_b32 s0, s0, 1
	v_or_b32_e32 v0, s6, v47
	v_lshl_add_u64 v[34:35], v[4:5], 0, s[0:1]
	v_lshlrev_b32_e32 v0, 11, v0
	v_lshl_add_u64 v[66:67], v[34:35], 0, v[0:1]
	v_or_b32_e32 v0, s6, v49
	s_waitcnt lgkmcnt(6)
	v_cvt_pk_bf16_f32 v30, v38, v36
	s_waitcnt lgkmcnt(4)
	v_cvt_pk_bf16_f32 v31, v40, v42
	s_waitcnt lgkmcnt(2)
	v_cvt_pk_bf16_f32 v32, v44, v60
	s_waitcnt lgkmcnt(0)
	v_cvt_pk_bf16_f32 v33, v62, v64
	v_lshlrev_b32_e32 v0, 11, v0
	global_store_dwordx4 v[66:67], v[30:33], off
	s_nop 1
	v_cvt_pk_bf16_f32 v30, v39, v37
	v_cvt_pk_bf16_f32 v31, v41, v43
	v_cvt_pk_bf16_f32 v32, v45, v61
	v_cvt_pk_bf16_f32 v33, v63, v65
	v_lshl_add_u64 v[36:37], v[34:35], 0, v[0:1]
	global_store_dwordx4 v[36:37], v[30:33], off
	ds_read2_b32 v[36:37], v48 offset0:49 offset1:57
	ds_read2_b32 v[38:39], v48 offset0:16 offset1:24
	ds_read2_b32 v[40:41], v48 offset0:82 offset1:90
	ds_read2_b32 v[42:43], v48 offset0:115 offset1:123
	ds_read2_b32 v[44:45], v48 offset0:148 offset1:156
	ds_read2_b32 v[60:61], v48 offset0:181 offset1:189
	ds_read2_b32 v[62:63], v48 offset0:214 offset1:222
	ds_read2_b32 v[64:65], v48 offset0:247 offset1:255
	v_or_b32_e32 v0, s6, v50
	v_lshlrev_b32_e32 v0, 11, v0
	v_lshl_add_u64 v[66:67], v[34:35], 0, v[0:1]
	v_or_b32_e32 v0, s6, v51
	s_waitcnt lgkmcnt(6)
	v_cvt_pk_bf16_f32 v30, v38, v36
	s_waitcnt lgkmcnt(4)
	v_cvt_pk_bf16_f32 v31, v40, v42
	s_waitcnt lgkmcnt(2)
	v_cvt_pk_bf16_f32 v32, v44, v60
	s_waitcnt lgkmcnt(0)
	v_cvt_pk_bf16_f32 v33, v62, v64
	v_lshlrev_b32_e32 v0, 11, v0
	global_store_dwordx4 v[66:67], v[30:33], off
	v_lshl_add_u64 v[34:35], v[34:35], 0, v[0:1]
	s_nop 0
	v_cvt_pk_bf16_f32 v30, v39, v37
	v_cvt_pk_bf16_f32 v31, v41, v43
	v_cvt_pk_bf16_f32 v32, v45, v61
	v_cvt_pk_bf16_f32 v33, v63, v65
	global_store_dwordx4 v[34:35], v[30:33], off
	s_waitcnt lgkmcnt(0)

.LBB0_463:
	v_lshl_add_u64 v[60:61], v[44:45], 0, s[6:7]
	global_load_dword v72, v[60:61], off nt
	v_lshl_add_u64 v[60:61], v[42:43], 0, s[6:7]
	global_load_dword v73, v[60:61], off nt
	v_lshl_add_u64 v[60:61], v[40:41], 0, s[6:7]
	global_load_dword v74, v[60:61], off nt
	v_lshl_add_u64 v[60:61], v[38:39], 0, s[6:7]
	global_load_dword v75, v[60:61], off nt
	v_lshl_add_u64 v[60:61], v[36:37], 0, s[6:7]
	global_load_dword v76, v[60:61], off nt
	v_lshl_add_u64 v[60:61], v[34:35], 0, s[6:7]
	global_load_dword v77, v[60:61], off nt
	v_lshl_add_u64 v[60:61], v[32:33], 0, s[6:7]
	global_load_dword v78, v[60:61], off nt
	v_lshl_add_u64 v[60:61], v[30:31], 0, s[6:7]
	global_load_dword v79, v[60:61], off nt
	s_add_u32 s6, s6, 0x60000
	s_addc_u32 s7, s7, 0
	v_lshl_add_u64 v[60:61], v[44:45], 0, s[6:7]
	global_load_dword v80, v[60:61], off nt
	v_lshl_add_u64 v[60:61], v[42:43], 0, s[6:7]
	global_load_dword v81, v[60:61], off nt
	v_lshl_add_u64 v[60:61], v[40:41], 0, s[6:7]
	global_load_dword v82, v[60:61], off nt
	v_lshl_add_u64 v[60:61], v[38:39], 0, s[6:7]
	global_load_dword v83, v[60:61], off nt
	v_lshl_add_u64 v[60:61], v[36:37], 0, s[6:7]
	global_load_dword v84, v[60:61], off nt
	v_lshl_add_u64 v[60:61], v[34:35], 0, s[6:7]
	global_load_dword v85, v[60:61], off nt
	v_lshl_add_u64 v[60:61], v[32:33], 0, s[6:7]
	global_load_dword v86, v[60:61], off nt
	v_lshl_add_u64 v[60:61], v[30:31], 0, s[6:7]
	global_load_dword v87, v[60:61], off nt
	s_add_u32 s6, s6, 0x60000
	s_addc_u32 s7, s7, 0
	v_lshl_add_u64 v[60:61], v[44:45], 0, s[6:7]
	global_load_dword v88, v[60:61], off nt
	v_lshl_add_u64 v[60:61], v[42:43], 0, s[6:7]
	global_load_dword v89, v[60:61], off nt
	v_lshl_add_u64 v[60:61], v[40:41], 0, s[6:7]
	global_load_dword v90, v[60:61], off nt
	v_lshl_add_u64 v[60:61], v[38:39], 0, s[6:7]
	global_load_dword v91, v[60:61], off nt
	v_lshl_add_u64 v[60:61], v[36:37], 0, s[6:7]
	global_load_dword v92, v[60:61], off nt
	v_lshl_add_u64 v[60:61], v[34:35], 0, s[6:7]
	global_load_dword v93, v[60:61], off nt
	v_lshl_add_u64 v[60:61], v[32:33], 0, s[6:7]
	global_load_dword v94, v[60:61], off nt
	v_lshl_add_u64 v[60:61], v[30:31], 0, s[6:7]
	global_load_dword v95, v[60:61], off nt
	s_add_u32 s6, s6, 0x60000
	s_addc_u32 s7, s7, 0
	v_lshl_add_u64 v[60:61], v[44:45], 0, s[6:7]
	global_load_dword v96, v[60:61], off nt
	v_lshl_add_u64 v[60:61], v[42:43], 0, s[6:7]
	global_load_dword v97, v[60:61], off nt
	v_lshl_add_u64 v[60:61], v[40:41], 0, s[6:7]
	global_load_dword v98, v[60:61], off nt
	v_lshl_add_u64 v[60:61], v[38:39], 0, s[6:7]
	global_load_dword v99, v[60:61], off nt
	v_lshl_add_u64 v[60:61], v[36:37], 0, s[6:7]
	global_load_dword v100, v[60:61], off nt
	v_lshl_add_u64 v[60:61], v[34:35], 0, s[6:7]
	global_load_dword v101, v[60:61], off nt
	v_lshl_add_u64 v[60:61], v[32:33], 0, s[6:7]
	global_load_dword v102, v[60:61], off nt
	v_lshl_add_u64 v[60:61], v[30:31], 0, s[6:7]
	global_load_dword v103, v[60:61], off nt
	s_add_u32 s6, s6, 0x60000
	s_addc_u32 s7, s7, 0
	v_add_u32_e32 v63, 0x400, v0
	s_waitcnt vmcnt(30)
	ds_write2_b32 v0, v72, v73 offset1:66
	s_waitcnt vmcnt(28)
	ds_write2_b32 v0, v74, v75 offset0:132 offset1:198
	s_waitcnt vmcnt(26)
	ds_write2_b32 v63, v76, v77 offset0:8 offset1:74
	s_waitcnt vmcnt(24)
	ds_write2_b32 v63, v78, v79 offset0:140 offset1:206
	v_add_u32_e32 v0, 0x840, v0
	v_add_u32_e32 v63, 0x400, v0
	s_waitcnt vmcnt(22)
	ds_write2_b32 v0, v80, v81 offset1:66
	s_waitcnt vmcnt(20)
	ds_write2_b32 v0, v82, v83 offset0:132 offset1:198
	s_waitcnt vmcnt(18)
	ds_write2_b32 v63, v84, v85 offset0:8 offset1:74
	s_waitcnt vmcnt(16)
	ds_write2_b32 v63, v86, v87 offset0:140 offset1:206
	v_add_u32_e32 v0, 0x840, v0
	v_add_u32_e32 v63, 0x400, v0
	s_waitcnt vmcnt(14)
	ds_write2_b32 v0, v88, v89 offset1:66
	s_waitcnt vmcnt(12)
	ds_write2_b32 v0, v90, v91 offset0:132 offset1:198
	s_waitcnt vmcnt(10)
	ds_write2_b32 v63, v92, v93 offset0:8 offset1:74
	s_waitcnt vmcnt(8)
	ds_write2_b32 v63, v94, v95 offset0:140 offset1:206
	v_add_u32_e32 v0, 0x840, v0
	v_add_u32_e32 v63, 0x400, v0
	s_waitcnt vmcnt(6)
	ds_write2_b32 v0, v96, v97 offset1:66
	s_waitcnt vmcnt(4)
	ds_write2_b32 v0, v98, v99 offset0:132 offset1:198
	s_waitcnt vmcnt(2)
	ds_write2_b32 v63, v100, v101 offset0:8 offset1:74
	s_waitcnt vmcnt(0)
	ds_write2_b32 v63, v102, v103 offset0:140 offset1:206
	v_add_u32_e32 v0, 0x840, v0
	s_and_b32 s0, 0xffff, s11
	s_and_b32 s6, 0xffff, s10
	s_cmpk_gt_u32 s6, 0x5f
	s_cselect_b32 s6, 0xfffff400, 0
	s_cselect_b32 s7, 0x400, 0
	s_add_i32 s6, s6, s0
	s_waitcnt lgkmcnt(0)
	s_lshl_b32 s6, s6, 1
	s_and_b32 s0, s0, 0x3e0
	s_and_b32 s6, s6, 0xfffff800
	s_or_b32 s0, s0, s7
	ds_read2_b32 v[36:37], v48 offset0:33 offset1:41
	ds_read2_b32 v[38:39], v48 offset1:8
	ds_read2_b32 v[40:41], v48 offset0:66 offset1:74
	ds_read2_b32 v[42:43], v48 offset0:99 offset1:107
	ds_read2_b32 v[44:45], v48 offset0:132 offset1:140
	ds_read2_b32 v[60:61], v48 offset0:165 offset1:173
	ds_read2_b32 v[62:63], v48 offset0:198 offset1:206
	ds_read2_b32 v[64:65], v48 offset0:231 offset1:239
	s_or_b32 s6, s0, s6
	s_and_b32 s0, 0xffff, s9
	v_or_b32_e32 v66, s6, v47
	s_lshl_b32 s0, s0, 1
	v_ashrrev_i32_e32 v67, 31, v66
	v_lshl_add_u64 v[34:35], v[6:7], 0, s[0:1]
	v_lshlrev_b64 v[66:67], 11, v[66:67]
	s_waitcnt lgkmcnt(6)
	v_cvt_pk_bf16_f32 v30, v38, v36
	s_waitcnt lgkmcnt(4)
	v_cvt_pk_bf16_f32 v31, v40, v42
	s_waitcnt lgkmcnt(2)
	v_cvt_pk_bf16_f32 v32, v44, v60
	s_waitcnt lgkmcnt(0)
	v_cvt_pk_bf16_f32 v33, v62, v64
	v_lshl_add_u64 v[66:67], v[34:35], 0, v[66:67]
	v_or_b32_e32 v36, s6, v49
	global_store_dwordx4 v[66:67], v[30:33], off
	v_or_b32_e32 v66, s6, v50
	v_ashrrev_i32_e32 v67, 31, v66
	v_cvt_pk_bf16_f32 v30, v39, v37
	v_ashrrev_i32_e32 v37, 31, v36
	v_lshlrev_b64 v[36:37], 11, v[36:37]
	v_cvt_pk_bf16_f32 v31, v41, v43
	v_cvt_pk_bf16_f32 v32, v45, v61
	v_cvt_pk_bf16_f32 v33, v63, v65
	v_lshl_add_u64 v[36:37], v[34:35], 0, v[36:37]
	global_store_dwordx4 v[36:37], v[30:33], off
	ds_read2_b32 v[36:37], v48 offset0:49 offset1:57
	ds_read2_b32 v[38:39], v48 offset0:16 offset1:24
	ds_read2_b32 v[40:41], v48 offset0:82 offset1:90
	ds_read2_b32 v[42:43], v48 offset0:115 offset1:123
	ds_read2_b32 v[44:45], v48 offset0:148 offset1:156
	ds_read2_b32 v[60:61], v48 offset0:181 offset1:189
	ds_read2_b32 v[62:63], v48 offset0:214 offset1:222
	ds_read2_b32 v[64:65], v48 offset0:247 offset1:255
	v_lshlrev_b64 v[66:67], 11, v[66:67]
	s_waitcnt lgkmcnt(6)
	v_cvt_pk_bf16_f32 v30, v38, v36
	s_waitcnt lgkmcnt(4)
	v_cvt_pk_bf16_f32 v31, v40, v42
	s_waitcnt lgkmcnt(2)
	v_cvt_pk_bf16_f32 v32, v44, v60
	s_waitcnt lgkmcnt(0)
	v_cvt_pk_bf16_f32 v33, v62, v64
	v_lshl_add_u64 v[66:67], v[34:35], 0, v[66:67]
	v_or_b32_e32 v36, s6, v51
	global_store_dwordx4 v[66:67], v[30:33], off
	s_nop 1
	v_cvt_pk_bf16_f32 v30, v39, v37
	v_ashrrev_i32_e32 v37, 31, v36
	v_lshlrev_b64 v[36:37], 11, v[36:37]
	v_cvt_pk_bf16_f32 v31, v41, v43
	v_cvt_pk_bf16_f32 v32, v45, v61
	v_cvt_pk_bf16_f32 v33, v63, v65
	v_lshl_add_u64 v[34:35], v[34:35], 0, v[36:37]
	global_store_dwordx4 v[34:35], v[30:33], off
	s_waitcnt lgkmcnt(0)

.LBB0_468:
	v_lshl_add_u64 v[60:61], v[44:45], 0, s[6:7]
	global_load_dword v72, v[60:61], off nt
	v_lshl_add_u64 v[60:61], v[42:43], 0, s[6:7]
	global_load_dword v73, v[60:61], off nt
	v_lshl_add_u64 v[60:61], v[40:41], 0, s[6:7]
	global_load_dword v74, v[60:61], off nt
	v_lshl_add_u64 v[60:61], v[38:39], 0, s[6:7]
	global_load_dword v75, v[60:61], off nt
	v_lshl_add_u64 v[60:61], v[36:37], 0, s[6:7]
	global_load_dword v76, v[60:61], off nt
	v_lshl_add_u64 v[60:61], v[34:35], 0, s[6:7]
	global_load_dword v77, v[60:61], off nt
	v_lshl_add_u64 v[60:61], v[32:33], 0, s[6:7]
	global_load_dword v78, v[60:61], off nt
	v_lshl_add_u64 v[60:61], v[30:31], 0, s[6:7]
	global_load_dword v79, v[60:61], off nt
	s_add_u32 s6, s6, 0x10000
	s_addc_u32 s7, s7, 0
	v_lshl_add_u64 v[60:61], v[44:45], 0, s[6:7]
	global_load_dword v80, v[60:61], off nt
	v_lshl_add_u64 v[60:61], v[42:43], 0, s[6:7]
	global_load_dword v81, v[60:61], off nt
	v_lshl_add_u64 v[60:61], v[40:41], 0, s[6:7]
	global_load_dword v82, v[60:61], off nt
	v_lshl_add_u64 v[60:61], v[38:39], 0, s[6:7]
	global_load_dword v83, v[60:61], off nt
	v_lshl_add_u64 v[60:61], v[36:37], 0, s[6:7]
	global_load_dword v84, v[60:61], off nt
	v_lshl_add_u64 v[60:61], v[34:35], 0, s[6:7]
	global_load_dword v85, v[60:61], off nt
	v_lshl_add_u64 v[60:61], v[32:33], 0, s[6:7]
	global_load_dword v86, v[60:61], off nt
	v_lshl_add_u64 v[60:61], v[30:31], 0, s[6:7]
	global_load_dword v87, v[60:61], off nt
	s_add_u32 s6, s6, 0x10000
	s_addc_u32 s7, s7, 0
	v_lshl_add_u64 v[60:61], v[44:45], 0, s[6:7]
	global_load_dword v88, v[60:61], off nt
	v_lshl_add_u64 v[60:61], v[42:43], 0, s[6:7]
	global_load_dword v89, v[60:61], off nt
	v_lshl_add_u64 v[60:61], v[40:41], 0, s[6:7]
	global_load_dword v90, v[60:61], off nt
	v_lshl_add_u64 v[60:61], v[38:39], 0, s[6:7]
	global_load_dword v91, v[60:61], off nt
	v_lshl_add_u64 v[60:61], v[36:37], 0, s[6:7]
	global_load_dword v92, v[60:61], off nt
	v_lshl_add_u64 v[60:61], v[34:35], 0, s[6:7]
	global_load_dword v93, v[60:61], off nt
	v_lshl_add_u64 v[60:61], v[32:33], 0, s[6:7]
	global_load_dword v94, v[60:61], off nt
	v_lshl_add_u64 v[60:61], v[30:31], 0, s[6:7]
	global_load_dword v95, v[60:61], off nt
	s_add_u32 s6, s6, 0x10000
	s_addc_u32 s7, s7, 0
	v_lshl_add_u64 v[60:61], v[44:45], 0, s[6:7]
	global_load_dword v96, v[60:61], off nt
	v_lshl_add_u64 v[60:61], v[42:43], 0, s[6:7]
	global_load_dword v97, v[60:61], off nt
	v_lshl_add_u64 v[60:61], v[40:41], 0, s[6:7]
	global_load_dword v98, v[60:61], off nt
	v_lshl_add_u64 v[60:61], v[38:39], 0, s[6:7]
	global_load_dword v99, v[60:61], off nt
	v_lshl_add_u64 v[60:61], v[36:37], 0, s[6:7]
	global_load_dword v100, v[60:61], off nt
	v_lshl_add_u64 v[60:61], v[34:35], 0, s[6:7]
	global_load_dword v101, v[60:61], off nt
	v_lshl_add_u64 v[60:61], v[32:33], 0, s[6:7]
	global_load_dword v102, v[60:61], off nt
	v_lshl_add_u64 v[60:61], v[30:31], 0, s[6:7]
	global_load_dword v103, v[60:61], off nt
	s_add_u32 s6, s6, 0x10000
	s_addc_u32 s7, s7, 0
	v_add_u32_e32 v63, 0x400, v0
	s_waitcnt vmcnt(30)
	ds_write2_b32 v0, v72, v73 offset1:66
	s_waitcnt vmcnt(28)
	ds_write2_b32 v0, v74, v75 offset0:132 offset1:198
	s_waitcnt vmcnt(26)
	ds_write2_b32 v63, v76, v77 offset0:8 offset1:74
	s_waitcnt vmcnt(24)
	ds_write2_b32 v63, v78, v79 offset0:140 offset1:206
	v_add_u32_e32 v0, 0x840, v0
	v_add_u32_e32 v63, 0x400, v0
	s_waitcnt vmcnt(22)
	ds_write2_b32 v0, v80, v81 offset1:66
	s_waitcnt vmcnt(20)
	ds_write2_b32 v0, v82, v83 offset0:132 offset1:198
	s_waitcnt vmcnt(18)
	ds_write2_b32 v63, v84, v85 offset0:8 offset1:74
	s_waitcnt vmcnt(16)
	ds_write2_b32 v63, v86, v87 offset0:140 offset1:206
	v_add_u32_e32 v0, 0x840, v0
	v_add_u32_e32 v63, 0x400, v0
	s_waitcnt vmcnt(14)
	ds_write2_b32 v0, v88, v89 offset1:66
	s_waitcnt vmcnt(12)
	ds_write2_b32 v0, v90, v91 offset0:132 offset1:198
	s_waitcnt vmcnt(10)
	ds_write2_b32 v63, v92, v93 offset0:8 offset1:74
	s_waitcnt vmcnt(8)
	ds_write2_b32 v63, v94, v95 offset0:140 offset1:206
	v_add_u32_e32 v0, 0x840, v0
	v_add_u32_e32 v63, 0x400, v0
	s_waitcnt vmcnt(6)
	ds_write2_b32 v0, v96, v97 offset1:66
	s_waitcnt vmcnt(4)
	ds_write2_b32 v0, v98, v99 offset0:132 offset1:198
	s_waitcnt vmcnt(2)
	ds_write2_b32 v63, v100, v101 offset0:8 offset1:74
	s_waitcnt vmcnt(0)
	ds_write2_b32 v63, v102, v103 offset0:140 offset1:206
	v_add_u32_e32 v0, 0x840, v0
	s_lshl_b32 s0, s16, 1
	s_waitcnt lgkmcnt(0)
	s_add_i32 s0, s0, 0x1c900
	s_lshl_b32 s6, s16, 5
	ds_read2_b32 v[36:37], v48 offset0:33 offset1:41
	ds_read2_b32 v[38:39], v48 offset1:8
	ds_read2_b32 v[40:41], v48 offset0:66 offset1:74
	ds_read2_b32 v[42:43], v48 offset0:99 offset1:107
	ds_read2_b32 v[44:45], v48 offset0:132 offset1:140
	ds_read2_b32 v[60:61], v48 offset0:165 offset1:173
	ds_read2_b32 v[62:63], v48 offset0:198 offset1:206
	ds_read2_b32 v[64:65], v48 offset0:231 offset1:239
	s_and_b32 s0, s0, 0x1ffc0
	s_and_b32 s6, s6, 0x3e0
	s_lshl_b32 s0, s0, 1
	v_or_b32_e32 v0, s6, v47
	v_lshl_add_u64 v[34:35], v[8:9], 0, s[0:1]
	v_mul_u32_u24_e32 v0, 0xb00, v0
	v_lshl_add_u64 v[66:67], v[0:1], 1, v[34:35]
	v_or_b32_e32 v0, s6, v49
	s_waitcnt lgkmcnt(6)
	v_cvt_pk_bf16_f32 v30, v38, v36
	s_waitcnt lgkmcnt(4)
	v_cvt_pk_bf16_f32 v31, v40, v42
	s_waitcnt lgkmcnt(2)
	v_cvt_pk_bf16_f32 v32, v44, v60
	s_waitcnt lgkmcnt(0)
	v_cvt_pk_bf16_f32 v33, v62, v64
	v_mul_u32_u24_e32 v0, 0xb00, v0
	global_store_dwordx4 v[66:67], v[30:33], off
	s_nop 1
	v_cvt_pk_bf16_f32 v30, v39, v37
	v_cvt_pk_bf16_f32 v31, v41, v43
	v_cvt_pk_bf16_f32 v32, v45, v61
	v_cvt_pk_bf16_f32 v33, v63, v65
	v_lshl_add_u64 v[36:37], v[0:1], 1, v[34:35]
	global_store_dwordx4 v[36:37], v[30:33], off
	ds_read2_b32 v[36:37], v48 offset0:16 offset1:24
	ds_read2_b32 v[38:39], v48 offset0:49 offset1:57
	ds_read2_b32 v[40:41], v48 offset0:82 offset1:90
	ds_read2_b32 v[42:43], v48 offset0:115 offset1:123
	ds_read2_b32 v[44:45], v48 offset0:148 offset1:156
	ds_read2_b32 v[60:61], v48 offset0:181 offset1:189
	ds_read2_b32 v[62:63], v48 offset0:214 offset1:222
	ds_read2_b32 v[64:65], v48 offset0:247 offset1:255
	v_or_b32_e32 v0, s6, v50
	v_mul_u32_u24_e32 v0, 0xb00, v0
	v_lshl_add_u64 v[66:67], v[0:1], 1, v[34:35]
	v_or_b32_e32 v0, s6, v51
	s_waitcnt lgkmcnt(6)
	v_cvt_pk_bf16_f32 v30, v36, v38
	s_waitcnt lgkmcnt(4)
	v_cvt_pk_bf16_f32 v31, v40, v42
	s_waitcnt lgkmcnt(2)
	v_cvt_pk_bf16_f32 v32, v44, v60
	s_waitcnt lgkmcnt(0)
	v_cvt_pk_bf16_f32 v33, v62, v64
	v_mul_u32_u24_e32 v0, 0xb00, v0
	global_store_dwordx4 v[66:67], v[30:33], off
	v_lshl_add_u64 v[34:35], v[0:1], 1, v[34:35]
	s_nop 0
	v_cvt_pk_bf16_f32 v30, v37, v39
	v_cvt_pk_bf16_f32 v31, v41, v43
	v_cvt_pk_bf16_f32 v32, v45, v61
	v_cvt_pk_bf16_f32 v33, v63, v65
	global_store_dwordx4 v[34:35], v[30:33], off
	s_waitcnt lgkmcnt(0)

.LBB0_473:
	v_lshl_add_u64 v[60:61], v[44:45], 0, s[6:7]
	global_load_dword v72, v[60:61], off nt
	v_lshl_add_u64 v[60:61], v[42:43], 0, s[6:7]
	global_load_dword v73, v[60:61], off nt
	v_lshl_add_u64 v[60:61], v[40:41], 0, s[6:7]
	global_load_dword v74, v[60:61], off nt
	v_lshl_add_u64 v[60:61], v[38:39], 0, s[6:7]
	global_load_dword v75, v[60:61], off nt
	v_lshl_add_u64 v[60:61], v[36:37], 0, s[6:7]
	global_load_dword v76, v[60:61], off nt
	v_lshl_add_u64 v[60:61], v[34:35], 0, s[6:7]
	global_load_dword v77, v[60:61], off nt
	v_lshl_add_u64 v[60:61], v[32:33], 0, s[6:7]
	global_load_dword v78, v[60:61], off nt
	v_lshl_add_u64 v[60:61], v[30:31], 0, s[6:7]
	global_load_dword v79, v[60:61], off nt
	s_add_u32 s6, s6, 0x10000
	s_addc_u32 s7, s7, 0
	v_lshl_add_u64 v[60:61], v[44:45], 0, s[6:7]
	global_load_dword v80, v[60:61], off nt
	v_lshl_add_u64 v[60:61], v[42:43], 0, s[6:7]
	global_load_dword v81, v[60:61], off nt
	v_lshl_add_u64 v[60:61], v[40:41], 0, s[6:7]
	global_load_dword v82, v[60:61], off nt
	v_lshl_add_u64 v[60:61], v[38:39], 0, s[6:7]
	global_load_dword v83, v[60:61], off nt
	v_lshl_add_u64 v[60:61], v[36:37], 0, s[6:7]
	global_load_dword v84, v[60:61], off nt
	v_lshl_add_u64 v[60:61], v[34:35], 0, s[6:7]
	global_load_dword v85, v[60:61], off nt
	v_lshl_add_u64 v[60:61], v[32:33], 0, s[6:7]
	global_load_dword v86, v[60:61], off nt
	v_lshl_add_u64 v[60:61], v[30:31], 0, s[6:7]
	global_load_dword v87, v[60:61], off nt
	s_add_u32 s6, s6, 0x10000
	s_addc_u32 s7, s7, 0
	v_lshl_add_u64 v[60:61], v[44:45], 0, s[6:7]
	global_load_dword v88, v[60:61], off nt
	v_lshl_add_u64 v[60:61], v[42:43], 0, s[6:7]
	global_load_dword v89, v[60:61], off nt
	v_lshl_add_u64 v[60:61], v[40:41], 0, s[6:7]
	global_load_dword v90, v[60:61], off nt
	v_lshl_add_u64 v[60:61], v[38:39], 0, s[6:7]
	global_load_dword v91, v[60:61], off nt
	v_lshl_add_u64 v[60:61], v[36:37], 0, s[6:7]
	global_load_dword v92, v[60:61], off nt
	v_lshl_add_u64 v[60:61], v[34:35], 0, s[6:7]
	global_load_dword v93, v[60:61], off nt
	v_lshl_add_u64 v[60:61], v[32:33], 0, s[6:7]
	global_load_dword v94, v[60:61], off nt
	v_lshl_add_u64 v[60:61], v[30:31], 0, s[6:7]
	global_load_dword v95, v[60:61], off nt
	s_add_u32 s6, s6, 0x10000
	s_addc_u32 s7, s7, 0
	v_lshl_add_u64 v[60:61], v[44:45], 0, s[6:7]
	global_load_dword v96, v[60:61], off nt
	v_lshl_add_u64 v[60:61], v[42:43], 0, s[6:7]
	global_load_dword v97, v[60:61], off nt
	v_lshl_add_u64 v[60:61], v[40:41], 0, s[6:7]
	global_load_dword v98, v[60:61], off nt
	v_lshl_add_u64 v[60:61], v[38:39], 0, s[6:7]
	global_load_dword v99, v[60:61], off nt
	v_lshl_add_u64 v[60:61], v[36:37], 0, s[6:7]
	global_load_dword v100, v[60:61], off nt
	v_lshl_add_u64 v[60:61], v[34:35], 0, s[6:7]
	global_load_dword v101, v[60:61], off nt
	v_lshl_add_u64 v[60:61], v[32:33], 0, s[6:7]
	global_load_dword v102, v[60:61], off nt
	v_lshl_add_u64 v[60:61], v[30:31], 0, s[6:7]
	global_load_dword v103, v[60:61], off nt
	s_add_u32 s6, s6, 0x10000
	s_addc_u32 s7, s7, 0
	v_add_u32_e32 v63, 0x400, v0
	s_waitcnt vmcnt(30)
	ds_write2_b32 v0, v72, v73 offset1:66
	s_waitcnt vmcnt(28)
	ds_write2_b32 v0, v74, v75 offset0:132 offset1:198
	s_waitcnt vmcnt(26)
	ds_write2_b32 v63, v76, v77 offset0:8 offset1:74
	s_waitcnt vmcnt(24)
	ds_write2_b32 v63, v78, v79 offset0:140 offset1:206
	v_add_u32_e32 v0, 0x840, v0
	v_add_u32_e32 v63, 0x400, v0
	s_waitcnt vmcnt(22)
	ds_write2_b32 v0, v80, v81 offset1:66
	s_waitcnt vmcnt(20)
	ds_write2_b32 v0, v82, v83 offset0:132 offset1:198
	s_waitcnt vmcnt(18)
	ds_write2_b32 v63, v84, v85 offset0:8 offset1:74
	s_waitcnt vmcnt(16)
	ds_write2_b32 v63, v86, v87 offset0:140 offset1:206
	v_add_u32_e32 v0, 0x840, v0
	v_add_u32_e32 v63, 0x400, v0
	s_waitcnt vmcnt(14)
	ds_write2_b32 v0, v88, v89 offset1:66
	s_waitcnt vmcnt(12)
	ds_write2_b32 v0, v90, v91 offset0:132 offset1:198
	s_waitcnt vmcnt(10)
	ds_write2_b32 v63, v92, v93 offset0:8 offset1:74
	s_waitcnt vmcnt(8)
	ds_write2_b32 v63, v94, v95 offset0:140 offset1:206
	v_add_u32_e32 v0, 0x840, v0
	v_add_u32_e32 v63, 0x400, v0
	s_waitcnt vmcnt(6)
	ds_write2_b32 v0, v96, v97 offset1:66
	s_waitcnt vmcnt(4)
	ds_write2_b32 v0, v98, v99 offset0:132 offset1:198
	s_waitcnt vmcnt(2)
	ds_write2_b32 v63, v100, v101 offset0:8 offset1:74
	s_waitcnt vmcnt(0)
	ds_write2_b32 v63, v102, v103 offset0:140 offset1:206
	v_add_u32_e32 v0, 0x840, v0
	s_lshl_b32 s0, s16, 1
	s_waitcnt lgkmcnt(0)
	s_add_i32 s0, s0, 0x1d400
	s_lshl_b32 s6, s16, 5
	ds_read2_b32 v[36:37], v48 offset0:33 offset1:41
	ds_read2_b32 v[38:39], v48 offset1:8
	ds_read2_b32 v[40:41], v48 offset0:66 offset1:74
	ds_read2_b32 v[42:43], v48 offset0:99 offset1:107
	ds_read2_b32 v[44:45], v48 offset0:132 offset1:140
	ds_read2_b32 v[60:61], v48 offset0:165 offset1:173
	ds_read2_b32 v[62:63], v48 offset0:198 offset1:206
	ds_read2_b32 v[64:65], v48 offset0:231 offset1:239
	s_and_b32 s0, s0, 0x1ffc0
	s_and_b32 s6, s6, 0x3e0
	s_lshl_b32 s0, s0, 1
	v_or_b32_e32 v0, s6, v47
	v_lshl_add_u64 v[34:35], v[10:11], 0, s[0:1]
	v_mul_u32_u24_e32 v0, 0xb00, v0
	v_lshl_add_u64 v[66:67], v[0:1], 1, v[34:35]
	v_or_b32_e32 v0, s6, v49
	s_waitcnt lgkmcnt(6)
	v_cvt_pk_bf16_f32 v30, v38, v36
	s_waitcnt lgkmcnt(4)
	v_cvt_pk_bf16_f32 v31, v40, v42
	s_waitcnt lgkmcnt(2)
	v_cvt_pk_bf16_f32 v32, v44, v60
	s_waitcnt lgkmcnt(0)
	v_cvt_pk_bf16_f32 v33, v62, v64
	v_mul_u32_u24_e32 v0, 0xb00, v0
	global_store_dwordx4 v[66:67], v[30:33], off
	s_nop 1
	v_cvt_pk_bf16_f32 v30, v39, v37
	v_cvt_pk_bf16_f32 v31, v41, v43
	v_cvt_pk_bf16_f32 v32, v45, v61
	v_cvt_pk_bf16_f32 v33, v63, v65
	v_lshl_add_u64 v[36:37], v[0:1], 1, v[34:35]
	global_store_dwordx4 v[36:37], v[30:33], off
	ds_read2_b32 v[36:37], v48 offset0:16 offset1:24
	ds_read2_b32 v[38:39], v48 offset0:49 offset1:57
	ds_read2_b32 v[40:41], v48 offset0:82 offset1:90
	ds_read2_b32 v[42:43], v48 offset0:115 offset1:123
	ds_read2_b32 v[44:45], v48 offset0:148 offset1:156
	ds_read2_b32 v[60:61], v48 offset0:181 offset1:189
	ds_read2_b32 v[62:63], v48 offset0:214 offset1:222
	ds_read2_b32 v[64:65], v48 offset0:247 offset1:255
	v_or_b32_e32 v0, s6, v50
	v_mul_u32_u24_e32 v0, 0xb00, v0
	v_lshl_add_u64 v[66:67], v[0:1], 1, v[34:35]
	v_or_b32_e32 v0, s6, v51
	s_waitcnt lgkmcnt(6)
	v_cvt_pk_bf16_f32 v30, v36, v38
	s_waitcnt lgkmcnt(4)
	v_cvt_pk_bf16_f32 v31, v40, v42
	s_waitcnt lgkmcnt(2)
	v_cvt_pk_bf16_f32 v32, v44, v60
	s_waitcnt lgkmcnt(0)
	v_cvt_pk_bf16_f32 v33, v62, v64
	v_mul_u32_u24_e32 v0, 0xb00, v0
	global_store_dwordx4 v[66:67], v[30:33], off
	v_lshl_add_u64 v[34:35], v[0:1], 1, v[34:35]
	s_nop 0
	v_cvt_pk_bf16_f32 v30, v37, v39
	v_cvt_pk_bf16_f32 v31, v41, v43
	v_cvt_pk_bf16_f32 v32, v45, v61
	v_cvt_pk_bf16_f32 v33, v63, v65
	global_store_dwordx4 v[34:35], v[30:33], off
	s_waitcnt lgkmcnt(0)

.LBB0_478:
	v_lshl_add_u64 v[60:61], v[44:45], 0, s[6:7]
	global_load_dword v72, v[60:61], off nt
	v_lshl_add_u64 v[60:61], v[42:43], 0, s[6:7]
	global_load_dword v73, v[60:61], off nt
	v_lshl_add_u64 v[60:61], v[40:41], 0, s[6:7]
	global_load_dword v74, v[60:61], off nt
	v_lshl_add_u64 v[60:61], v[38:39], 0, s[6:7]
	global_load_dword v75, v[60:61], off nt
	v_lshl_add_u64 v[60:61], v[36:37], 0, s[6:7]
	global_load_dword v76, v[60:61], off nt
	v_lshl_add_u64 v[60:61], v[34:35], 0, s[6:7]
	global_load_dword v77, v[60:61], off nt
	v_lshl_add_u64 v[60:61], v[32:33], 0, s[6:7]
	global_load_dword v78, v[60:61], off nt
	v_lshl_add_u64 v[60:61], v[30:31], 0, s[6:7]
	global_load_dword v79, v[60:61], off nt
	s_add_u32 s6, s6, 0x58000
	s_addc_u32 s7, s7, 0
	v_lshl_add_u64 v[60:61], v[44:45], 0, s[6:7]
	global_load_dword v80, v[60:61], off nt
	v_lshl_add_u64 v[60:61], v[42:43], 0, s[6:7]
	global_load_dword v81, v[60:61], off nt
	v_lshl_add_u64 v[60:61], v[40:41], 0, s[6:7]
	global_load_dword v82, v[60:61], off nt
	v_lshl_add_u64 v[60:61], v[38:39], 0, s[6:7]
	global_load_dword v83, v[60:61], off nt
	v_lshl_add_u64 v[60:61], v[36:37], 0, s[6:7]
	global_load_dword v84, v[60:61], off nt
	v_lshl_add_u64 v[60:61], v[34:35], 0, s[6:7]
	global_load_dword v85, v[60:61], off nt
	v_lshl_add_u64 v[60:61], v[32:33], 0, s[6:7]
	global_load_dword v86, v[60:61], off nt
	v_lshl_add_u64 v[60:61], v[30:31], 0, s[6:7]
	global_load_dword v87, v[60:61], off nt
	s_add_u32 s6, s6, 0x58000
	s_addc_u32 s7, s7, 0
	v_lshl_add_u64 v[60:61], v[44:45], 0, s[6:7]
	global_load_dword v88, v[60:61], off nt
	v_lshl_add_u64 v[60:61], v[42:43], 0, s[6:7]
	global_load_dword v89, v[60:61], off nt
	v_lshl_add_u64 v[60:61], v[40:41], 0, s[6:7]
	global_load_dword v90, v[60:61], off nt
	v_lshl_add_u64 v[60:61], v[38:39], 0, s[6:7]
	global_load_dword v91, v[60:61], off nt
	v_lshl_add_u64 v[60:61], v[36:37], 0, s[6:7]
	global_load_dword v92, v[60:61], off nt
	v_lshl_add_u64 v[60:61], v[34:35], 0, s[6:7]
	global_load_dword v93, v[60:61], off nt
	v_lshl_add_u64 v[60:61], v[32:33], 0, s[6:7]
	global_load_dword v94, v[60:61], off nt
	v_lshl_add_u64 v[60:61], v[30:31], 0, s[6:7]
	global_load_dword v95, v[60:61], off nt
	s_add_u32 s6, s6, 0x58000
	s_addc_u32 s7, s7, 0
	v_lshl_add_u64 v[60:61], v[44:45], 0, s[6:7]
	global_load_dword v96, v[60:61], off nt
	v_lshl_add_u64 v[60:61], v[42:43], 0, s[6:7]
	global_load_dword v97, v[60:61], off nt
	v_lshl_add_u64 v[60:61], v[40:41], 0, s[6:7]
	global_load_dword v98, v[60:61], off nt
	v_lshl_add_u64 v[60:61], v[38:39], 0, s[6:7]
	global_load_dword v99, v[60:61], off nt
	v_lshl_add_u64 v[60:61], v[36:37], 0, s[6:7]
	global_load_dword v100, v[60:61], off nt
	v_lshl_add_u64 v[60:61], v[34:35], 0, s[6:7]
	global_load_dword v101, v[60:61], off nt
	v_lshl_add_u64 v[60:61], v[32:33], 0, s[6:7]
	global_load_dword v102, v[60:61], off nt
	v_lshl_add_u64 v[60:61], v[30:31], 0, s[6:7]
	global_load_dword v103, v[60:61], off nt
	s_add_u32 s6, s6, 0x58000
	s_addc_u32 s7, s7, 0
	v_add_u32_e32 v63, 0x400, v0
	s_waitcnt vmcnt(30)
	ds_write2_b32 v0, v72, v73 offset1:66
	s_waitcnt vmcnt(28)
	ds_write2_b32 v0, v74, v75 offset0:132 offset1:198
	s_waitcnt vmcnt(26)
	ds_write2_b32 v63, v76, v77 offset0:8 offset1:74
	s_waitcnt vmcnt(24)
	ds_write2_b32 v63, v78, v79 offset0:140 offset1:206
	v_add_u32_e32 v0, 0x840, v0
	v_add_u32_e32 v63, 0x400, v0
	s_waitcnt vmcnt(22)
	ds_write2_b32 v0, v80, v81 offset1:66
	s_waitcnt vmcnt(20)
	ds_write2_b32 v0, v82, v83 offset0:132 offset1:198
	s_waitcnt vmcnt(18)
	ds_write2_b32 v63, v84, v85 offset0:8 offset1:74
	s_waitcnt vmcnt(16)
	ds_write2_b32 v63, v86, v87 offset0:140 offset1:206
	v_add_u32_e32 v0, 0x840, v0
	v_add_u32_e32 v63, 0x400, v0
	s_waitcnt vmcnt(14)
	ds_write2_b32 v0, v88, v89 offset1:66
	s_waitcnt vmcnt(12)
	ds_write2_b32 v0, v90, v91 offset0:132 offset1:198
	s_waitcnt vmcnt(10)
	ds_write2_b32 v63, v92, v93 offset0:8 offset1:74
	s_waitcnt vmcnt(8)
	ds_write2_b32 v63, v94, v95 offset0:140 offset1:206
	v_add_u32_e32 v0, 0x840, v0
	v_add_u32_e32 v63, 0x400, v0
	s_waitcnt vmcnt(6)
	ds_write2_b32 v0, v96, v97 offset1:66
	s_waitcnt vmcnt(4)
	ds_write2_b32 v0, v98, v99 offset0:132 offset1:198
	s_waitcnt vmcnt(2)
	ds_write2_b32 v63, v100, v101 offset0:8 offset1:74
	s_waitcnt vmcnt(0)
	ds_write2_b32 v63, v102, v103 offset0:140 offset1:206
	v_add_u32_e32 v0, 0x840, v0
	s_and_b32 s0, 0xffff, s10
	s_and_b32 s6, 0xffff, s9
	s_cmpk_gt_u32 s6, 0x57
	s_cselect_b32 s6, 0xfffff500, 0
	s_cselect_b32 s7, 0x80, 0
	s_add_i32 s6, s6, s0
	s_waitcnt lgkmcnt(0)
	s_lshl_b32 s6, s6, 1
	s_and_b32 s0, s0, 0x60
	s_and_b32 s6, s6, 0xffffff00
	s_or_b32 s0, s0, s7
	ds_read2_b32 v[36:37], v48 offset0:33 offset1:41
	ds_read2_b32 v[38:39], v48 offset1:8
	ds_read2_b32 v[40:41], v48 offset0:66 offset1:74
	ds_read2_b32 v[42:43], v48 offset0:99 offset1:107
	ds_read2_b32 v[44:45], v48 offset0:132 offset1:140
	ds_read2_b32 v[60:61], v48 offset0:165 offset1:173
	ds_read2_b32 v[62:63], v48 offset0:198 offset1:206
	ds_read2_b32 v[64:65], v48 offset0:231 offset1:239
	s_or_b32 s6, s0, s6
	s_and_b32 s0, 0xffff, s8
	v_or_b32_e32 v66, s6, v47
	s_lshl_b32 s0, s0, 1
	v_ashrrev_i32_e32 v67, 31, v66
	v_lshl_add_u64 v[34:35], v[12:13], 0, s[0:1]
	v_lshlrev_b64 v[66:67], 11, v[66:67]
	s_waitcnt lgkmcnt(6)
	v_cvt_pk_bf16_f32 v30, v38, v36
	s_waitcnt lgkmcnt(4)
	v_cvt_pk_bf16_f32 v31, v40, v42
	s_waitcnt lgkmcnt(2)
	v_cvt_pk_bf16_f32 v32, v44, v60
	s_waitcnt lgkmcnt(0)
	v_cvt_pk_bf16_f32 v33, v62, v64
	v_lshl_add_u64 v[66:67], v[34:35], 0, v[66:67]
	v_or_b32_e32 v36, s6, v49
	global_store_dwordx4 v[66:67], v[30:33], off
	v_or_b32_e32 v66, s6, v50
	v_ashrrev_i32_e32 v67, 31, v66
	v_cvt_pk_bf16_f32 v30, v39, v37
	v_ashrrev_i32_e32 v37, 31, v36
	v_lshlrev_b64 v[36:37], 11, v[36:37]
	v_cvt_pk_bf16_f32 v31, v41, v43
	v_cvt_pk_bf16_f32 v32, v45, v61
	v_cvt_pk_bf16_f32 v33, v63, v65
	v_lshl_add_u64 v[36:37], v[34:35], 0, v[36:37]
	global_store_dwordx4 v[36:37], v[30:33], off
	ds_read2_b32 v[36:37], v48 offset0:49 offset1:57
	ds_read2_b32 v[38:39], v48 offset0:16 offset1:24
	ds_read2_b32 v[40:41], v48 offset0:82 offset1:90
	ds_read2_b32 v[42:43], v48 offset0:115 offset1:123
	ds_read2_b32 v[44:45], v48 offset0:148 offset1:156
	ds_read2_b32 v[60:61], v48 offset0:181 offset1:189
	ds_read2_b32 v[62:63], v48 offset0:214 offset1:222
	ds_read2_b32 v[64:65], v48 offset0:247 offset1:255
	v_lshlrev_b64 v[66:67], 11, v[66:67]
	s_waitcnt lgkmcnt(6)
	v_cvt_pk_bf16_f32 v30, v38, v36
	s_waitcnt lgkmcnt(4)
	v_cvt_pk_bf16_f32 v31, v40, v42
	s_waitcnt lgkmcnt(2)
	v_cvt_pk_bf16_f32 v32, v44, v60
	s_waitcnt lgkmcnt(0)
	v_cvt_pk_bf16_f32 v33, v62, v64
	v_lshl_add_u64 v[66:67], v[34:35], 0, v[66:67]
	v_or_b32_e32 v36, s6, v51
	global_store_dwordx4 v[66:67], v[30:33], off
	s_nop 1
	v_cvt_pk_bf16_f32 v30, v39, v37
	v_ashrrev_i32_e32 v37, 31, v36
	v_lshlrev_b64 v[36:37], 11, v[36:37]
	v_cvt_pk_bf16_f32 v31, v41, v43
	v_cvt_pk_bf16_f32 v32, v45, v61
	v_cvt_pk_bf16_f32 v33, v63, v65
	v_lshl_add_u64 v[34:35], v[34:35], 0, v[36:37]
	global_store_dwordx4 v[34:35], v[30:33], off
	s_waitcnt lgkmcnt(0)

.LBB0_483:
	v_lshl_add_u64 v[60:61], v[44:45], 0, s[10:11]
	global_load_dword v72, v[60:61], off nt
	v_lshl_add_u64 v[60:61], v[42:43], 0, s[10:11]
	global_load_dword v73, v[60:61], off nt
	v_lshl_add_u64 v[60:61], v[40:41], 0, s[10:11]
	global_load_dword v74, v[60:61], off nt
	v_lshl_add_u64 v[60:61], v[38:39], 0, s[10:11]
	global_load_dword v75, v[60:61], off nt
	v_lshl_add_u64 v[60:61], v[36:37], 0, s[10:11]
	global_load_dword v76, v[60:61], off nt
	v_lshl_add_u64 v[60:61], v[34:35], 0, s[10:11]
	global_load_dword v77, v[60:61], off nt
	v_lshl_add_u64 v[60:61], v[32:33], 0, s[10:11]
	global_load_dword v78, v[60:61], off nt
	v_lshl_add_u64 v[60:61], v[30:31], 0, s[10:11]
	global_load_dword v79, v[60:61], off nt
	s_add_u32 s10, s10, 0x58000
	s_addc_u32 s11, s11, 0
	v_lshl_add_u64 v[60:61], v[44:45], 0, s[10:11]
	global_load_dword v80, v[60:61], off nt
	v_lshl_add_u64 v[60:61], v[42:43], 0, s[10:11]
	global_load_dword v81, v[60:61], off nt
	v_lshl_add_u64 v[60:61], v[40:41], 0, s[10:11]
	global_load_dword v82, v[60:61], off nt
	v_lshl_add_u64 v[60:61], v[38:39], 0, s[10:11]
	global_load_dword v83, v[60:61], off nt
	v_lshl_add_u64 v[60:61], v[36:37], 0, s[10:11]
	global_load_dword v84, v[60:61], off nt
	v_lshl_add_u64 v[60:61], v[34:35], 0, s[10:11]
	global_load_dword v85, v[60:61], off nt
	v_lshl_add_u64 v[60:61], v[32:33], 0, s[10:11]
	global_load_dword v86, v[60:61], off nt
	v_lshl_add_u64 v[60:61], v[30:31], 0, s[10:11]
	global_load_dword v87, v[60:61], off nt
	s_add_u32 s10, s10, 0x58000
	s_addc_u32 s11, s11, 0
	v_lshl_add_u64 v[60:61], v[44:45], 0, s[10:11]
	global_load_dword v88, v[60:61], off nt
	v_lshl_add_u64 v[60:61], v[42:43], 0, s[10:11]
	global_load_dword v89, v[60:61], off nt
	v_lshl_add_u64 v[60:61], v[40:41], 0, s[10:11]
	global_load_dword v90, v[60:61], off nt
	v_lshl_add_u64 v[60:61], v[38:39], 0, s[10:11]
	global_load_dword v91, v[60:61], off nt
	v_lshl_add_u64 v[60:61], v[36:37], 0, s[10:11]
	global_load_dword v92, v[60:61], off nt
	v_lshl_add_u64 v[60:61], v[34:35], 0, s[10:11]
	global_load_dword v93, v[60:61], off nt
	v_lshl_add_u64 v[60:61], v[32:33], 0, s[10:11]
	global_load_dword v94, v[60:61], off nt
	v_lshl_add_u64 v[60:61], v[30:31], 0, s[10:11]
	global_load_dword v95, v[60:61], off nt
	s_add_u32 s10, s10, 0x58000
	s_addc_u32 s11, s11, 0
	v_lshl_add_u64 v[60:61], v[44:45], 0, s[10:11]
	global_load_dword v96, v[60:61], off nt
	v_lshl_add_u64 v[60:61], v[42:43], 0, s[10:11]
	global_load_dword v97, v[60:61], off nt
	v_lshl_add_u64 v[60:61], v[40:41], 0, s[10:11]
	global_load_dword v98, v[60:61], off nt
	v_lshl_add_u64 v[60:61], v[38:39], 0, s[10:11]
	global_load_dword v99, v[60:61], off nt
	v_lshl_add_u64 v[60:61], v[36:37], 0, s[10:11]
	global_load_dword v100, v[60:61], off nt
	v_lshl_add_u64 v[60:61], v[34:35], 0, s[10:11]
	global_load_dword v101, v[60:61], off nt
	v_lshl_add_u64 v[60:61], v[32:33], 0, s[10:11]
	global_load_dword v102, v[60:61], off nt
	v_lshl_add_u64 v[60:61], v[30:31], 0, s[10:11]
	global_load_dword v103, v[60:61], off nt
	s_add_u32 s10, s10, 0x58000
	s_addc_u32 s11, s11, 0
	v_add_u32_e32 v63, 0x400, v0
	s_waitcnt vmcnt(30)
	ds_write2_b32 v0, v72, v73 offset1:66
	s_waitcnt vmcnt(28)
	ds_write2_b32 v0, v74, v75 offset0:132 offset1:198
	s_waitcnt vmcnt(26)
	ds_write2_b32 v63, v76, v77 offset0:8 offset1:74
	s_waitcnt vmcnt(24)
	ds_write2_b32 v63, v78, v79 offset0:140 offset1:206
	v_add_u32_e32 v0, 0x840, v0
	v_add_u32_e32 v63, 0x400, v0
	s_waitcnt vmcnt(22)
	ds_write2_b32 v0, v80, v81 offset1:66
	s_waitcnt vmcnt(20)
	ds_write2_b32 v0, v82, v83 offset0:132 offset1:198
	s_waitcnt vmcnt(18)
	ds_write2_b32 v63, v84, v85 offset0:8 offset1:74
	s_waitcnt vmcnt(16)
	ds_write2_b32 v63, v86, v87 offset0:140 offset1:206
	v_add_u32_e32 v0, 0x840, v0
	v_add_u32_e32 v63, 0x400, v0
	s_waitcnt vmcnt(14)
	ds_write2_b32 v0, v88, v89 offset1:66
	s_waitcnt vmcnt(12)
	ds_write2_b32 v0, v90, v91 offset0:132 offset1:198
	s_waitcnt vmcnt(10)
	ds_write2_b32 v63, v92, v93 offset0:8 offset1:74
	s_waitcnt vmcnt(8)
	ds_write2_b32 v63, v94, v95 offset0:140 offset1:206
	v_add_u32_e32 v0, 0x840, v0
	v_add_u32_e32 v63, 0x400, v0
	s_waitcnt vmcnt(6)
	ds_write2_b32 v0, v96, v97 offset1:66
	s_waitcnt vmcnt(4)
	ds_write2_b32 v0, v98, v99 offset0:132 offset1:198
	s_waitcnt vmcnt(2)
	ds_write2_b32 v63, v100, v101 offset0:8 offset1:74
	s_waitcnt vmcnt(0)
	ds_write2_b32 v63, v102, v103 offset0:140 offset1:206
	v_add_u32_e32 v0, 0x840, v0
	s_cmpk_gt_i32 s0, 0x57
	s_cselect_b32 s0, 0xfffff500, 0
	s_cselect_b32 s7, 0x80, 0
	s_add_i32 s0, s0, s8
	s_waitcnt lgkmcnt(0)
	s_lshl_b32 s0, s0, 1
	s_and_b32 s8, s8, 0x60
	s_and_b32 s0, s0, 0xffffff00
	s_or_b32 s7, s8, s7
	ds_read2_b32 v[36:37], v48 offset0:33 offset1:41
	ds_read2_b32 v[38:39], v48 offset1:8
	ds_read2_b32 v[40:41], v48 offset0:66 offset1:74
	ds_read2_b32 v[42:43], v48 offset0:99 offset1:107
	ds_read2_b32 v[44:45], v48 offset0:132 offset1:140
	ds_read2_b32 v[60:61], v48 offset0:165 offset1:173
	ds_read2_b32 v[62:63], v48 offset0:198 offset1:206
	ds_read2_b32 v[64:65], v48 offset0:231 offset1:239
	s_or_b32 s0, s7, s0
	v_or_b32_e32 v66, s0, v47
	s_ashr_i32 s7, s6, 31
	v_ashrrev_i32_e32 v67, 31, v66
	v_lshl_add_u64 v[34:35], s[6:7], 1, v[14:15]
	v_lshlrev_b64 v[66:67], 11, v[66:67]
	s_waitcnt lgkmcnt(6)
	v_cvt_pk_bf16_f32 v30, v38, v36
	s_waitcnt lgkmcnt(4)
	v_cvt_pk_bf16_f32 v31, v40, v42
	s_waitcnt lgkmcnt(2)
	v_cvt_pk_bf16_f32 v32, v44, v60
	s_waitcnt lgkmcnt(0)
	v_cvt_pk_bf16_f32 v33, v62, v64
	v_lshl_add_u64 v[66:67], v[34:35], 0, v[66:67]
	v_or_b32_e32 v36, s0, v49
	global_store_dwordx4 v[66:67], v[30:33], off
	v_or_b32_e32 v66, s0, v50
	v_ashrrev_i32_e32 v67, 31, v66
	v_cvt_pk_bf16_f32 v30, v39, v37
	v_ashrrev_i32_e32 v37, 31, v36
	v_lshlrev_b64 v[36:37], 11, v[36:37]
	v_cvt_pk_bf16_f32 v31, v41, v43
	v_cvt_pk_bf16_f32 v32, v45, v61
	v_cvt_pk_bf16_f32 v33, v63, v65
	v_lshl_add_u64 v[36:37], v[34:35], 0, v[36:37]
	global_store_dwordx4 v[36:37], v[30:33], off
	ds_read2_b32 v[36:37], v48 offset0:49 offset1:57
	ds_read2_b32 v[38:39], v48 offset0:16 offset1:24
	ds_read2_b32 v[40:41], v48 offset0:82 offset1:90
	ds_read2_b32 v[42:43], v48 offset0:115 offset1:123
	ds_read2_b32 v[44:45], v48 offset0:148 offset1:156
	ds_read2_b32 v[60:61], v48 offset0:181 offset1:189
	ds_read2_b32 v[62:63], v48 offset0:214 offset1:222
	ds_read2_b32 v[64:65], v48 offset0:247 offset1:255
	v_lshlrev_b64 v[66:67], 11, v[66:67]
	s_waitcnt lgkmcnt(6)
	v_cvt_pk_bf16_f32 v30, v38, v36
	s_waitcnt lgkmcnt(4)
	v_cvt_pk_bf16_f32 v31, v40, v42
	s_waitcnt lgkmcnt(2)
	v_cvt_pk_bf16_f32 v32, v44, v60
	s_waitcnt lgkmcnt(0)
	v_cvt_pk_bf16_f32 v33, v62, v64
	v_lshl_add_u64 v[66:67], v[34:35], 0, v[66:67]
	v_or_b32_e32 v36, s0, v51
	global_store_dwordx4 v[66:67], v[30:33], off
	s_nop 1
	v_cvt_pk_bf16_f32 v30, v39, v37
	v_ashrrev_i32_e32 v37, 31, v36
	v_lshlrev_b64 v[36:37], 11, v[36:37]
	v_cvt_pk_bf16_f32 v31, v41, v43
	v_cvt_pk_bf16_f32 v32, v45, v61
	v_cvt_pk_bf16_f32 v33, v63, v65
	v_lshl_add_u64 v[34:35], v[34:35], 0, v[36:37]
	global_store_dwordx4 v[34:35], v[30:33], off
	s_waitcnt lgkmcnt(0)
	s_branch .LBB0_446
